# P7 K-loop: first trip after an epilogue uses vmcnt(24) at its first two waits so the 16 write-through epilogue stores stay in flight behind the older tile loads
# speedup vs baseline: 1.0037x; 1.0024x over previous
; #define LAS __attribute__((address_space(3)))
; __global__ void __launch_bounds__(512, 2) mk_fwd(Args a) {
;     extern __shared__ __attribute__((aligned(16))) unsigned char lds_raw[];
;     LAS unsigned char* lds = (LAS unsigned char*)lds_raw;
;     cg::grid_group grid = cg::this_grid();
;     const int G = gridDim.x;
;     if (threadIdx.x < 2) ((volatile LAS unsigned*)(lds + LDS_BARST))[threadIdx.x] = 0u;
;     __syncthreads();
;     if (a.ws == nullptr) grid.sync();
;     const XcdBarrier xbar = xcd_barrier_post((unsigned*)(a.ws + WS_BAR), (volatile LAS unsigned*)(lds + LDS_BARST));
_Z6mk_fwd4Args:
	s_load_dwordx8 s[4:11], s[0:1], 0x80
	s_load_dwordx4 s[88:91], s[0:1], 0xa0
	s_load_dword s18, s[0:1], 0xb0
	s_mov_b32 s3, 0
	v_writelane_b32 v255, s3, 54
	v_writelane_b32 v255, 0, 55
	v_writelane_b32 v253, s2, 0
	v_and_b32_e32 v236, 0x3ff, v0
	v_cmp_gt_u32_e32 vcc, 2, v236
	s_waitcnt lgkmcnt(0)
	v_writelane_b32 v253, s4, 1
	s_nop 1
	v_writelane_b32 v253, s5, 2
	v_writelane_b32 v253, s6, 3
	v_writelane_b32 v253, s7, 4
	v_writelane_b32 v253, s8, 5
	v_writelane_b32 v253, s9, 6
	v_writelane_b32 v253, s10, 7
	v_writelane_b32 v253, s11, 8
	s_add_u32 s4, s0, 0xa8
	s_addc_u32 s5, s1, 0
	s_and_saveexec_b64 s[2:3], vcc
	v_lshl_add_u32 v1, v236, 2, 0
	v_add_u32_e32 v1, 0x23fc0, v1
	v_mov_b32_e32 v2, 0
	ds_write_b32 v1, v2
	s_or_b64 exec, exec, s[2:3]
	s_cmp_lg_u64 s[88:89], 0
	s_waitcnt lgkmcnt(0)
	s_barrier
	s_cbranch_scc1 .LBB0_14
	v_lshrrev_b32_e32 v1, 20, v0
	v_lshrrev_b32_e32 v0, 10, v0
	v_or_b32_e32 v0, v0, v1
	s_movk_i32 s2, 0x3ff
	v_and_or_b32 v0, v0, s2, v236
	v_cmp_eq_u32_e32 vcc, 0, v0
	s_barrier
	s_and_saveexec_b64 s[2:3], vcc
	s_cbranch_execz .LBB0_13
	buffer_wbl2 sc1
	s_load_dwordx2 s[4:5], s[4:5], 0x58
	s_mov_b64 s[6:7], exec
	v_mbcnt_lo_u32_b32 v0, s6, 0
	v_mbcnt_hi_u32_b32 v0, s7, v0
	v_cmp_eq_u32_e32 vcc, 0, v0
	s_waitcnt lgkmcnt(0)
	s_load_dword s10, s[4:5], 0x28
	s_and_saveexec_b64 s[8:9], vcc
	s_cbranch_execz .LBB0_6
	s_bcnt1_i32_b64 s6, s[6:7]
	v_mov_b32_e32 v1, 0
	v_mov_b32_e32 v2, s6
	global_atomic_add v1, v1, v2, s[4:5] offset:32 sc0

; template <class Epi, class Sched, bool ALIGN_EPI = true, bool SP2 = true, class Pre = NoPre>
; __device__ __forceinline__ void gemm_phase(LAS unsigned char* lds, const Gemm g, const Sched& S, const Epi& E, const Pre& pre = Pre()) {
;     ...
;     for (;;) {
;         const bool has_next = S.next(ui + 1, nxt);
;         const char* nA = has_next ? PG8_TILE_A(nxt) : cA; const char* nB = has_next ? PG8_TILE_B(nxt) : cB;
.LBB0_849:
	v_writelane_b32 v255, 1, 55
	s_mov_b64 s[10:11], 0

; #define PG8_STAGE(bufoff, gbase, voff) do { _Pragma("unroll") for (int _i = 0; _i < 2; ++_i) \
;         __builtin_amdgcn_global_load_lds((const unsigned*)((const char*)(gbase) + (voff)[_i]), (LAS unsigned*)(lds + (bufoff) + ldsw + _i * 8192), 16, 0, 0); } while (0)
; #define PG8_LDA(dst, b, h) do { _Pragma("unroll") for (int m = 0; m < 4; ++m) _Pragma("unroll") for (int k = 0; k < 2; ++k) dst[m][k] = *(const LAS bf16x8*)(lds + PG8_SA(b, h) + aoff + m * 2048 + k * 1024); } while (0)
; #define PG8_LDB(dst, b, h) do { _Pragma("unroll") for (int n = 0; n < 2; ++n) _Pragma("unroll") for (int k = 0; k < 2; ++k) dst[n][k] = *(const LAS bf16x8*)(lds + PG8_SB(b, h) + boff + n * 2048 + k * 1024); } while (0)
; #define PG8_MMA(ai, bj, At, Bt) do { __builtin_amdgcn_s_setprio(1); _Pragma("unroll") for (int m = 0; m < 4; ++m) _Pragma("unroll") for (int n = 0; n < 2; ++n) _Pragma("unroll") for (int k = 0; k < 2; ++k) \
;         acc[ai][bj][m][n] = __builtin_amdgcn_mfma_f32_16x16x32_bf16(Bt[n][k], At[m][k], acc[ai][bj][m][n], 0, 0, 0); __builtin_amdgcn_s_setprio(0); } while (0)
; #define PG8_WAIT_V(n) asm volatile("s_waitcnt vmcnt(" #n ")" ::: "memory")
; #define PG8_WAIT_L(n) asm volatile("s_waitcnt lgkmcnt(" #n ")" ::: "memory")
; #define PG8_BAR __builtin_amdgcn_s_barrier()
; #define PG8_SCHED __builtin_amdgcn_sched_barrier(0)
; template <class Epi, class Sched, bool ALIGN_EPI = true, bool SP2 = true, class Pre = NoPre>
; __device__ __forceinline__ void gemm_phase(LAS unsigned char* lds, const Gemm g, const Sched& S, const Epi& E, const Pre& pre = Pre()) {
;     ...
;             const bool last = (t == nt - 2);
;             const char* a1 = cA + (size_t)(t + 1) * kstep;
;             const char* a2 = last ? nA : cA + (size_t)(t + 2) * kstep; const char* b2 = last ? nB : cB + (size_t)(t + 2) * kstep;
;             const char* a3 = a2 + kstep; const char* b3 = b2 + kstep;
;             if constexpr (SP2) {
;             PG8_LDB(B0, 0, 0); PG8_LDB(B1, 0, 1); PG8_SCHED; PG8_LDA(At, 0, 0); PG8_STAGE(PG8_SA(1, 1), a1 + hsA, voffA);
;             PG8_WAIT_V(8); PG8_WAIT_L(0); PG8_BAR; PG8_MMA(0, 0, At, B0); PG8_MMA(0, 1, At, B1); PG8_BAR; PG8_SCHED;
.LBB0_858:
	s_add_u32 s10, s30, 0xfffc0080
	s_addc_u32 s11, s31, -1
	s_add_i32 s80, 0, 0x10000
	s_cmp_eq_u32 s58, 12
	s_cselect_b32 s39, s21, s11
	s_cselect_b32 s38, s45, s10
	s_cselect_b32 s11, s17, s53
	s_cselect_b32 s10, s46, s47
	s_add_i32 s82, 0, 0x14000
	v_add_u32_e32 v156, s80, v138
	v_add_u32_e32 v172, s82, v138
	ds_read_b128 v[144:147], v156
	ds_read_b128 v[148:151], v156 offset:1024
	ds_read_b128 v[152:155], v156 offset:2048
	ds_read_b128 v[156:159], v156 offset:3072
	ds_read_b128 v[160:163], v172
	ds_read_b128 v[164:167], v172 offset:1024
	ds_read_b128 v[168:171], v172 offset:2048
	ds_read_b128 v[172:175], v172 offset:3072
	v_lshl_add_u64 v[220:221], s[30:31], 0, v[136:137]
	s_add_i32 m0, s8, 0xc000
	ds_read_b128 v[176:179], v143
	ds_read_b128 v[180:183], v143 offset:1024
	ds_read_b128 v[184:187], v143 offset:2048
	ds_read_b128 v[188:191], v143 offset:3072
	ds_read_b128 v[192:195], v143 offset:4096
	ds_read_b128 v[196:199], v143 offset:5120
	ds_read_b128 v[212:215], v143 offset:6144
	ds_read_b128 v[216:219], v143 offset:7168
	global_load_lds_dwordx4 v[220:221], off
	v_lshl_add_u64 v[220:221], s[30:31], 0, v[134:135]
	s_add_i32 m0, s8, 0xe000
	s_nop 0
	global_load_lds_dwordx4 v[220:221], off
	s_cmp_lg_u32 s58, -2
	s_cbranch_scc1 .Lrx_n1
	v_readlane_b32 vcc_lo, v255, 55
	s_cmp_eq_u32 vcc_lo, 0
	s_cbranch_scc1 .Lrx_n1
	s_waitcnt vmcnt(24)
	s_branch .Lrx_j1

; #define PG8_STAGE(bufoff, gbase, voff) do { _Pragma("unroll") for (int _i = 0; _i < 2; ++_i) \
;         __builtin_amdgcn_global_load_lds((const unsigned*)((const char*)(gbase) + (voff)[_i]), (LAS unsigned*)(lds + (bufoff) + ldsw + _i * 8192), 16, 0, 0); } while (0)
; #define PG8_LDA(dst, b, h) do { _Pragma("unroll") for (int m = 0; m < 4; ++m) _Pragma("unroll") for (int k = 0; k < 2; ++k) dst[m][k] = *(const LAS bf16x8*)(lds + PG8_SA(b, h) + aoff + m * 2048 + k * 1024); } while (0)
; #define PG8_MMA(ai, bj, At, Bt) do { __builtin_amdgcn_s_setprio(1); _Pragma("unroll") for (int m = 0; m < 4; ++m) _Pragma("unroll") for (int n = 0; n < 2; ++n) _Pragma("unroll") for (int k = 0; k < 2; ++k) \
;         acc[ai][bj][m][n] = __builtin_amdgcn_mfma_f32_16x16x32_bf16(Bt[n][k], At[m][k], acc[ai][bj][m][n], 0, 0, 0); __builtin_amdgcn_s_setprio(0); } while (0)
; #define PG8_WAIT_V(n) asm volatile("s_waitcnt vmcnt(" #n ")" ::: "memory")
; #define PG8_WAIT_L(n) asm volatile("s_waitcnt lgkmcnt(" #n ")" ::: "memory")
; #define PG8_BAR __builtin_amdgcn_s_barrier()
; #define PG8_SCHED __builtin_amdgcn_sched_barrier(0)
; template <class Epi, class Sched, bool ALIGN_EPI = true, bool SP2 = true, class Pre = NoPre>
; __device__ __forceinline__ void gemm_phase(LAS unsigned char* lds, const Gemm g, const Sched& S, const Epi& E, const Pre& pre = Pre()) {
;     ...
;             PG8_WAIT_V(8); PG8_WAIT_L(0); PG8_BAR; PG8_MMA(0, 0, At, B0); PG8_MMA(0, 1, At, B1); PG8_BAR; PG8_SCHED;
;             PG8_LDA(At, 0, 1); PG8_STAGE(PG8_SB(0, 0), b2, voffB); PG8_STAGE(PG8_SB(0, 1), b2 + hsB, voffB); PG8_STAGE(PG8_SA(0, 0), a2, voffA);
;             PG8_WAIT_V(8); PG8_WAIT_L(0); PG8_BAR; PG8_MMA(1, 0, At, B0); PG8_MMA(1, 1, At, B1); PG8_BAR; PG8_SCHED;
.Lrx_j1:
	s_waitcnt lgkmcnt(0)
	s_barrier
	s_setprio 1
	s_waitcnt lgkmcnt(0)
	v_mfma_f32_16x16x32_bf16 v[124:127], v[144:147], v[176:179], v[124:127]
	v_mfma_f32_16x16x32_bf16 v[120:123], v[152:155], v[176:179], v[120:123]
	v_mfma_f32_16x16x32_bf16 v[108:111], v[144:147], v[184:187], v[108:111]
	v_mfma_f32_16x16x32_bf16 v[104:107], v[152:155], v[184:187], v[104:107]
	v_mfma_f32_16x16x32_bf16 v[92:95], v[144:147], v[192:195], v[92:95]
	v_mfma_f32_16x16x32_bf16 v[88:91], v[152:155], v[192:195], v[88:91]
	v_mfma_f32_16x16x32_bf16 v[76:79], v[144:147], v[212:215], v[76:79]
	v_mfma_f32_16x16x32_bf16 v[72:75], v[152:155], v[212:215], v[72:75]
	v_mfma_f32_16x16x32_bf16 v[124:127], v[148:151], v[180:183], v[124:127]
	v_mfma_f32_16x16x32_bf16 v[120:123], v[156:159], v[180:183], v[120:123]
	v_mfma_f32_16x16x32_bf16 v[108:111], v[148:151], v[188:191], v[108:111]
	v_mfma_f32_16x16x32_bf16 v[104:107], v[156:159], v[188:191], v[104:107]
	v_mfma_f32_16x16x32_bf16 v[92:95], v[148:151], v[196:199], v[92:95]
	v_mfma_f32_16x16x32_bf16 v[88:91], v[156:159], v[196:199], v[88:91]
	v_mfma_f32_16x16x32_bf16 v[76:79], v[148:151], v[216:219], v[76:79]
	v_mfma_f32_16x16x32_bf16 v[72:75], v[156:159], v[216:219], v[72:75]
	s_setprio 0
	s_setprio 1
	v_mfma_f32_16x16x32_bf16 v[116:119], v[160:163], v[176:179], v[116:119]
	v_mfma_f32_16x16x32_bf16 v[112:115], v[168:171], v[176:179], v[112:115]
	v_mfma_f32_16x16x32_bf16 v[100:103], v[160:163], v[184:187], v[100:103]
	v_mfma_f32_16x16x32_bf16 v[96:99], v[168:171], v[184:187], v[96:99]
	v_mfma_f32_16x16x32_bf16 v[84:87], v[160:163], v[192:195], v[84:87]
	v_mfma_f32_16x16x32_bf16 v[80:83], v[168:171], v[192:195], v[80:83]
	v_mfma_f32_16x16x32_bf16 v[68:71], v[160:163], v[212:215], v[68:71]
	v_mfma_f32_16x16x32_bf16 v[64:67], v[168:171], v[212:215], v[64:67]
	v_mfma_f32_16x16x32_bf16 v[116:119], v[164:167], v[180:183], v[116:119]
	v_mfma_f32_16x16x32_bf16 v[112:115], v[172:175], v[180:183], v[112:115]
	v_mfma_f32_16x16x32_bf16 v[100:103], v[164:167], v[188:191], v[100:103]
	v_mfma_f32_16x16x32_bf16 v[96:99], v[172:175], v[188:191], v[96:99]
	v_mfma_f32_16x16x32_bf16 v[84:87], v[164:167], v[196:199], v[84:87]
	v_mfma_f32_16x16x32_bf16 v[80:83], v[172:175], v[196:199], v[80:83]
	v_mfma_f32_16x16x32_bf16 v[68:71], v[164:167], v[216:219], v[68:71]
	v_mfma_f32_16x16x32_bf16 v[64:67], v[172:175], v[216:219], v[64:67]
	s_setprio 0
	s_barrier
	s_add_i32 s80, s80, s7
	v_lshl_add_u64 v[220:221], s[10:11], 0, v[200:201]
	s_mov_b32 m0, s80
	ds_read_b128 v[176:179], v143 offset:16384
	ds_read_b128 v[180:183], v143 offset:17408
	ds_read_b128 v[184:187], v143 offset:18432
	ds_read_b128 v[188:191], v143 offset:19456
	ds_read_b128 v[192:195], v143 offset:20480
	ds_read_b128 v[196:199], v143 offset:21504
	ds_read_b128 v[212:215], v143 offset:22528
	ds_read_b128 v[216:219], v143 offset:23552
	global_load_lds_dwordx4 v[220:221], off
	s_add_i32 m0, s80, 0x2000
	s_add_u32 s80, s10, 0x40000
	v_lshl_add_u64 v[222:223], s[10:11], 0, v[128:129]
	s_addc_u32 s81, s11, 0
	s_add_i32 s82, s82, s7
	global_load_lds_dwordx4 v[222:223], off
	v_lshl_add_u64 v[224:225], s[80:81], 0, v[200:201]
	s_mov_b32 m0, s82
	v_lshl_add_u64 v[226:227], s[38:39], 0, v[130:131]
	global_load_lds_dwordx4 v[224:225], off
	v_lshl_add_u64 v[224:225], s[80:81], 0, v[128:129]
	s_add_i32 m0, s82, 0x2000
	s_nop 0
	global_load_lds_dwordx4 v[224:225], off
	v_lshl_add_u64 v[224:225], s[38:39], 0, v[132:133]
	s_mov_b32 m0, s8
	s_nop 0
	global_load_lds_dwordx4 v[224:225], off
	s_mov_b32 m0, s9
	s_nop 0
	global_load_lds_dwordx4 v[226:227], off
	s_cmp_lg_u32 s58, -2
	s_cbranch_scc1 .Lrx_n2
	v_readlane_b32 vcc_lo, v255, 55
	s_cmp_eq_u32 vcc_lo, 0
	s_cbranch_scc1 .Lrx_n2
	s_waitcnt vmcnt(24)
	s_branch .Lrx_j2

; #define PG8_STAGE(bufoff, gbase, voff) do { _Pragma("unroll") for (int _i = 0; _i < 2; ++_i) \
;         __builtin_amdgcn_global_load_lds((const unsigned*)((const char*)(gbase) + (voff)[_i]), (LAS unsigned*)(lds + (bufoff) + ldsw + _i * 8192), 16, 0, 0); } while (0)
; #define PG8_LDA(dst, b, h) do { _Pragma("unroll") for (int m = 0; m < 4; ++m) _Pragma("unroll") for (int k = 0; k < 2; ++k) dst[m][k] = *(const LAS bf16x8*)(lds + PG8_SA(b, h) + aoff + m * 2048 + k * 1024); } while (0)
; #define PG8_LDB(dst, b, h) do { _Pragma("unroll") for (int n = 0; n < 2; ++n) _Pragma("unroll") for (int k = 0; k < 2; ++k) dst[n][k] = *(const LAS bf16x8*)(lds + PG8_SB(b, h) + boff + n * 2048 + k * 1024); } while (0)
; #define PG8_MMA(ai, bj, At, Bt) do { __builtin_amdgcn_s_setprio(1); _Pragma("unroll") for (int m = 0; m < 4; ++m) _Pragma("unroll") for (int n = 0; n < 2; ++n) _Pragma("unroll") for (int k = 0; k < 2; ++k) \
;         acc[ai][bj][m][n] = __builtin_amdgcn_mfma_f32_16x16x32_bf16(Bt[n][k], At[m][k], acc[ai][bj][m][n], 0, 0, 0); __builtin_amdgcn_s_setprio(0); } while (0)
; #define PG8_WAIT_V(n) asm volatile("s_waitcnt vmcnt(" #n ")" ::: "memory")
; #define PG8_WAIT_L(n) asm volatile("s_waitcnt lgkmcnt(" #n ")" ::: "memory")
; #define PG8_BAR __builtin_amdgcn_s_barrier()
; #define PG8_SCHED __builtin_amdgcn_sched_barrier(0)
; template <class Epi, class Sched, bool ALIGN_EPI = true, bool SP2 = true, class Pre = NoPre>
; __device__ __forceinline__ void gemm_phase(LAS unsigned char* lds, const Gemm g, const Sched& S, const Epi& E, const Pre& pre = Pre()) {
;     ...
;             PG8_WAIT_V(8); PG8_WAIT_L(0); PG8_BAR; PG8_MMA(1, 0, At, B0); PG8_MMA(1, 1, At, B1); PG8_BAR; PG8_SCHED;
;             PG8_LDB(B0, 1, 0); PG8_LDB(B1, 1, 1); PG8_SCHED; PG8_LDA(At, 1, 0); PG8_STAGE(PG8_SA(0, 1), a2 + hsA, voffA);
;             PG8_WAIT_V(8); PG8_WAIT_L(0); PG8_BAR; PG8_MMA(0, 0, At, B0); PG8_MMA(0, 1, At, B1); PG8_BAR; PG8_SCHED;
.Lrx_j2:
	s_waitcnt lgkmcnt(0)
	s_barrier
	s_setprio 1
	s_waitcnt lgkmcnt(0)
	v_mfma_f32_16x16x32_bf16 v[60:63], v[144:147], v[176:179], v[60:63]
	v_mfma_f32_16x16x32_bf16 v[56:59], v[152:155], v[176:179], v[56:59]
	v_mfma_f32_16x16x32_bf16 v[52:55], v[144:147], v[184:187], v[52:55]
	v_mfma_f32_16x16x32_bf16 v[44:47], v[152:155], v[184:187], v[44:47]
	v_mfma_f32_16x16x32_bf16 v[36:39], v[144:147], v[192:195], v[36:39]
	v_mfma_f32_16x16x32_bf16 v[28:31], v[152:155], v[192:195], v[28:31]
	v_mfma_f32_16x16x32_bf16 v[16:19], v[144:147], v[212:215], v[16:19]
	v_mfma_f32_16x16x32_bf16 v[8:11], v[152:155], v[212:215], v[8:11]
	v_mfma_f32_16x16x32_bf16 v[60:63], v[148:151], v[180:183], v[60:63]
	v_mfma_f32_16x16x32_bf16 v[56:59], v[156:159], v[180:183], v[56:59]
	v_mfma_f32_16x16x32_bf16 v[52:55], v[148:151], v[188:191], v[52:55]
	v_mfma_f32_16x16x32_bf16 v[44:47], v[156:159], v[188:191], v[44:47]
	v_mfma_f32_16x16x32_bf16 v[36:39], v[148:151], v[196:199], v[36:39]
	v_mfma_f32_16x16x32_bf16 v[28:31], v[156:159], v[196:199], v[28:31]
	v_mfma_f32_16x16x32_bf16 v[16:19], v[148:151], v[216:219], v[16:19]
	v_mfma_f32_16x16x32_bf16 v[8:11], v[156:159], v[216:219], v[8:11]
	s_setprio 0
	s_setprio 1
	v_mfma_f32_16x16x32_bf16 v[48:51], v[160:163], v[176:179], v[48:51]
	v_mfma_f32_16x16x32_bf16 v[40:43], v[168:171], v[176:179], v[40:43]
	v_mfma_f32_16x16x32_bf16 v[32:35], v[160:163], v[184:187], v[32:35]
	v_mfma_f32_16x16x32_bf16 v[24:27], v[168:171], v[184:187], v[24:27]
	v_mfma_f32_16x16x32_bf16 v[20:23], v[160:163], v[192:195], v[20:23]
	v_mfma_f32_16x16x32_bf16 v[12:15], v[168:171], v[192:195], v[12:15]
	v_mfma_f32_16x16x32_bf16 v[4:7], v[160:163], v[212:215], v[4:7]
	v_mfma_f32_16x16x32_bf16 v[0:3], v[168:171], v[212:215], v[0:3]
	v_mfma_f32_16x16x32_bf16 v[48:51], v[164:167], v[180:183], v[48:51]
	v_mfma_f32_16x16x32_bf16 v[40:43], v[172:175], v[180:183], v[40:43]
	v_mfma_f32_16x16x32_bf16 v[32:35], v[164:167], v[188:191], v[32:35]
	v_mfma_f32_16x16x32_bf16 v[24:27], v[172:175], v[188:191], v[24:27]
	v_mfma_f32_16x16x32_bf16 v[20:23], v[164:167], v[196:199], v[20:23]
	v_mfma_f32_16x16x32_bf16 v[12:15], v[172:175], v[196:199], v[12:15]
	v_mfma_f32_16x16x32_bf16 v[4:7], v[164:167], v[216:219], v[4:7]
	v_mfma_f32_16x16x32_bf16 v[0:3], v[172:175], v[216:219], v[0:3]
	s_setprio 0
	s_barrier
	s_add_i32 s80, 0, 0x18000
	s_add_i32 s81, 0, 0x1c000
	v_add_u32_e32 v156, s80, v138
	v_add_u32_e32 v172, s81, v138
	ds_read_b128 v[144:147], v156
	ds_read_b128 v[148:151], v156 offset:1024
	ds_read_b128 v[152:155], v156 offset:2048
	ds_read_b128 v[156:159], v156 offset:3072
	ds_read_b128 v[160:163], v172
	ds_read_b128 v[164:167], v172 offset:1024
	ds_read_b128 v[168:171], v172 offset:2048
	ds_read_b128 v[172:175], v172 offset:3072
	s_add_u32 s38, s38, 0x40000
	s_addc_u32 s39, s39, 0
	s_mov_b32 m0, s15
	v_lshl_add_u64 v[228:229], s[38:39], 0, v[132:133]
	ds_read_b128 v[176:179], v143 offset:32768
	ds_read_b128 v[180:183], v143 offset:33792
	ds_read_b128 v[184:187], v143 offset:34816
	ds_read_b128 v[188:191], v143 offset:35840
	ds_read_b128 v[192:195], v143 offset:36864
	ds_read_b128 v[196:199], v143 offset:37888
	ds_read_b128 v[212:215], v143 offset:38912
	ds_read_b128 v[216:219], v143 offset:39936
	global_load_lds_dwordx4 v[228:229], off
	v_lshl_add_u64 v[228:229], s[38:39], 0, v[130:131]
	s_mov_b32 m0, s27
	s_nop 0
	global_load_lds_dwordx4 v[228:229], off
	s_waitcnt vmcnt(8)
	s_waitcnt lgkmcnt(0)
	s_barrier
	s_setprio 1
	s_waitcnt lgkmcnt(0)
	v_mfma_f32_16x16x32_bf16 v[124:127], v[144:147], v[176:179], v[124:127]
	v_mfma_f32_16x16x32_bf16 v[120:123], v[152:155], v[176:179], v[120:123]
	v_mfma_f32_16x16x32_bf16 v[108:111], v[144:147], v[184:187], v[108:111]
	v_mfma_f32_16x16x32_bf16 v[104:107], v[152:155], v[184:187], v[104:107]
	v_mfma_f32_16x16x32_bf16 v[92:95], v[144:147], v[192:195], v[92:95]
	v_mfma_f32_16x16x32_bf16 v[88:91], v[152:155], v[192:195], v[88:91]
	v_mfma_f32_16x16x32_bf16 v[76:79], v[144:147], v[212:215], v[76:79]
	v_mfma_f32_16x16x32_bf16 v[72:75], v[152:155], v[212:215], v[72:75]
	v_mfma_f32_16x16x32_bf16 v[124:127], v[148:151], v[180:183], v[124:127]
	v_mfma_f32_16x16x32_bf16 v[120:123], v[156:159], v[180:183], v[120:123]
	v_mfma_f32_16x16x32_bf16 v[108:111], v[148:151], v[188:191], v[108:111]
	v_mfma_f32_16x16x32_bf16 v[104:107], v[156:159], v[188:191], v[104:107]
	v_mfma_f32_16x16x32_bf16 v[92:95], v[148:151], v[196:199], v[92:95]
	v_mfma_f32_16x16x32_bf16 v[88:91], v[156:159], v[196:199], v[88:91]
	v_mfma_f32_16x16x32_bf16 v[76:79], v[148:151], v[216:219], v[76:79]
	v_mfma_f32_16x16x32_bf16 v[72:75], v[156:159], v[216:219], v[72:75]
	s_setprio 0
	s_setprio 1
	v_mfma_f32_16x16x32_bf16 v[116:119], v[160:163], v[176:179], v[116:119]
	v_mfma_f32_16x16x32_bf16 v[112:115], v[168:171], v[176:179], v[112:115]
	v_mfma_f32_16x16x32_bf16 v[100:103], v[160:163], v[184:187], v[100:103]
	v_mfma_f32_16x16x32_bf16 v[96:99], v[168:171], v[184:187], v[96:99]
	v_mfma_f32_16x16x32_bf16 v[84:87], v[160:163], v[192:195], v[84:87]
	v_mfma_f32_16x16x32_bf16 v[80:83], v[168:171], v[192:195], v[80:83]
	v_mfma_f32_16x16x32_bf16 v[68:71], v[160:163], v[212:215], v[68:71]
	v_mfma_f32_16x16x32_bf16 v[64:67], v[168:171], v[212:215], v[64:67]
	v_mfma_f32_16x16x32_bf16 v[116:119], v[164:167], v[180:183], v[116:119]
	v_mfma_f32_16x16x32_bf16 v[112:115], v[172:175], v[180:183], v[112:115]
	v_mfma_f32_16x16x32_bf16 v[100:103], v[164:167], v[188:191], v[100:103]
	v_mfma_f32_16x16x32_bf16 v[96:99], v[172:175], v[188:191], v[96:99]
	v_mfma_f32_16x16x32_bf16 v[84:87], v[164:167], v[196:199], v[84:87]
	v_mfma_f32_16x16x32_bf16 v[80:83], v[172:175], v[196:199], v[80:83]
	v_mfma_f32_16x16x32_bf16 v[68:71], v[164:167], v[216:219], v[68:71]
	v_mfma_f32_16x16x32_bf16 v[64:67], v[172:175], v[216:219], v[64:67]
	s_setprio 0
	s_barrier
; #define PG8_STAGE(bufoff, gbase, voff) do { _Pragma("unroll") for (int _i = 0; _i < 2; ++_i) \
;         __builtin_amdgcn_global_load_lds((const unsigned*)((const char*)(gbase) + (voff)[_i]), (LAS unsigned*)(lds + (bufoff) + ldsw + _i * 8192), 16, 0, 0); } while (0)
; #define PG8_LDA(dst, b, h) do { _Pragma("unroll") for (int m = 0; m < 4; ++m) _Pragma("unroll") for (int k = 0; k < 2; ++k) dst[m][k] = *(const LAS bf16x8*)(lds + PG8_SA(b, h) + aoff + m * 2048 + k * 1024); } while (0)
; #define PG8_BAR __builtin_amdgcn_s_barrier()
; template <class Epi, class Sched, bool ALIGN_EPI = true, bool SP2 = true, class Pre = NoPre>
; __device__ __forceinline__ void gemm_phase(LAS unsigned char* lds, const Gemm g, const Sched& S, const Epi& E, const Pre& pre = Pre()) {
;     ...
;             PG8_LDA(At, 1, 1); PG8_STAGE(PG8_SB(1, 0), b3, voffB); PG8_STAGE(PG8_SB(1, 1), b3 + hsB, voffB); PG8_STAGE(PG8_SA(1, 0), a3, voffA);
;             PG8_WAIT_V(8); PG8_WAIT_L(0); PG8_BAR; PG8_MMA(1, 0, At, B0); PG8_MMA(1, 1, At, B1); PG8_BAR; PG8_SCHED;
;             } else {
;             PG8_LDB(B0, 0, 0); PG8_SCHED; PG8_LDA(At, 0, 0); PG8_STAGE(PG8_SA(1, 1), a1 + hsA, voffA);
;             PG8_WAIT_L(8); PG8_BAR; PG8_WAIT_L(0); PG8_MMA(0, 0, At, B0); PG8_BAR; PG8_SCHED;
;             PG8_LDB(B1, 0, 1); PG8_STAGE(PG8_SB(0, 0), b2, voffB);
;             PG8_BAR; PG8_WAIT_L(0); PG8_MMA(0, 1, At, B1); PG8_BAR;
;             PG8_LDA(At, 0, 1); PG8_STAGE(PG8_SA(0, 0), a2, voffA);
;             PG8_BAR; PG8_WAIT_L(0); PG8_MMA(1, 0, At, B0); PG8_BAR; PG8_SCHED;
;             PG8_STAGE(PG8_SB(0, 1), b2 + hsB, voffB);
;             PG8_WAIT_V(6); PG8_BAR; PG8_MMA(1, 1, At, B1); PG8_BAR;
;             PG8_LDB(B0, 1, 0); PG8_SCHED; PG8_LDA(At, 1, 0); PG8_STAGE(PG8_SA(0, 1), a2 + hsA, voffA);
;             PG8_WAIT_L(8); PG8_BAR; PG8_WAIT_L(0); PG8_MMA(0, 0, At, B0); PG8_BAR; PG8_SCHED;
;             PG8_LDB(B1, 1, 1); PG8_STAGE(PG8_SB(1, 0), b3, voffB);
;             PG8_BAR; PG8_WAIT_L(0); PG8_MMA(0, 1, At, B1); PG8_BAR;
;             PG8_LDA(At, 1, 1); PG8_STAGE(PG8_SA(1, 0), a3, voffA);
;             PG8_BAR; PG8_WAIT_L(0); PG8_MMA(1, 0, At, B0); PG8_BAR; PG8_SCHED;
;             PG8_STAGE(PG8_SB(1, 1), b3 + hsB, voffB);
;             PG8_WAIT_V(6); PG8_BAR; PG8_MMA(1, 1, At, B1); PG8_BAR;
;             }
;         }
;         if constexpr (ALIGN_EPI) { if (wr == 0) PG8_BAR; }
	s_add_i32 s38, s80, s7
	v_lshl_add_u64 v[220:221], v[220:221], 0, s[50:51]
	s_mov_b32 m0, s38
	ds_read_b128 v[176:179], v143 offset:49152
	ds_read_b128 v[180:183], v143 offset:50176
	ds_read_b128 v[184:187], v143 offset:51200
	ds_read_b128 v[188:191], v143 offset:52224
	ds_read_b128 v[192:195], v143 offset:53248
	ds_read_b128 v[196:199], v143 offset:54272
	ds_read_b128 v[212:215], v143 offset:55296
	ds_read_b128 v[216:219], v143 offset:56320
	global_load_lds_dwordx4 v[220:221], off
	s_add_i32 m0, s38, 0x2000
	s_add_u32 s10, s10, 0x40080
	v_lshl_add_u64 v[220:221], v[222:223], 0, s[50:51]
	s_addc_u32 s11, s11, 0
	s_add_i32 s38, s81, s7
	global_load_lds_dwordx4 v[220:221], off
	v_lshl_add_u64 v[220:221], s[10:11], 0, v[200:201]
	s_mov_b32 m0, s38
	s_nop 0
	global_load_lds_dwordx4 v[220:221], off
	v_lshl_add_u64 v[220:221], s[10:11], 0, v[128:129]
	s_add_i32 m0, s38, 0x2000
	s_nop 0
	global_load_lds_dwordx4 v[220:221], off
	v_lshl_add_u64 v[220:221], v[224:225], 0, s[50:51]
	s_mov_b32 m0, s29
	s_nop 0
	global_load_lds_dwordx4 v[220:221], off
	v_lshl_add_u64 v[220:221], v[226:227], 0, s[50:51]
	s_mov_b32 m0, s42
	s_nop 0
	global_load_lds_dwordx4 v[220:221], off
	s_waitcnt vmcnt(8)
	s_waitcnt lgkmcnt(0)
	s_barrier
	s_setprio 1
	s_waitcnt lgkmcnt(0)
	v_mfma_f32_16x16x32_bf16 v[60:63], v[144:147], v[176:179], v[60:63]
	v_mfma_f32_16x16x32_bf16 v[56:59], v[152:155], v[176:179], v[56:59]
	v_mfma_f32_16x16x32_bf16 v[52:55], v[144:147], v[184:187], v[52:55]
	v_mfma_f32_16x16x32_bf16 v[44:47], v[152:155], v[184:187], v[44:47]
	v_mfma_f32_16x16x32_bf16 v[36:39], v[144:147], v[192:195], v[36:39]
	v_mfma_f32_16x16x32_bf16 v[28:31], v[152:155], v[192:195], v[28:31]
	v_mfma_f32_16x16x32_bf16 v[16:19], v[144:147], v[212:215], v[16:19]
	v_mfma_f32_16x16x32_bf16 v[8:11], v[152:155], v[212:215], v[8:11]
	v_mfma_f32_16x16x32_bf16 v[60:63], v[148:151], v[180:183], v[60:63]
	v_mfma_f32_16x16x32_bf16 v[56:59], v[156:159], v[180:183], v[56:59]
	v_mfma_f32_16x16x32_bf16 v[52:55], v[148:151], v[188:191], v[52:55]
	v_mfma_f32_16x16x32_bf16 v[44:47], v[156:159], v[188:191], v[44:47]
	v_mfma_f32_16x16x32_bf16 v[36:39], v[148:151], v[196:199], v[36:39]
	v_mfma_f32_16x16x32_bf16 v[28:31], v[156:159], v[196:199], v[28:31]
	v_mfma_f32_16x16x32_bf16 v[16:19], v[148:151], v[216:219], v[16:19]
	v_mfma_f32_16x16x32_bf16 v[8:11], v[156:159], v[216:219], v[8:11]
	s_setprio 0
	s_setprio 1
	v_mfma_f32_16x16x32_bf16 v[48:51], v[160:163], v[176:179], v[48:51]
	v_mfma_f32_16x16x32_bf16 v[40:43], v[168:171], v[176:179], v[40:43]
	v_mfma_f32_16x16x32_bf16 v[32:35], v[160:163], v[184:187], v[32:35]
	v_mfma_f32_16x16x32_bf16 v[24:27], v[168:171], v[184:187], v[24:27]
	v_mfma_f32_16x16x32_bf16 v[20:23], v[160:163], v[192:195], v[20:23]
	v_mfma_f32_16x16x32_bf16 v[12:15], v[168:171], v[192:195], v[12:15]
	v_mfma_f32_16x16x32_bf16 v[4:7], v[160:163], v[212:215], v[4:7]
	v_mfma_f32_16x16x32_bf16 v[0:3], v[168:171], v[212:215], v[0:3]
	v_mfma_f32_16x16x32_bf16 v[48:51], v[164:167], v[180:183], v[48:51]
	v_mfma_f32_16x16x32_bf16 v[40:43], v[172:175], v[180:183], v[40:43]
	v_mfma_f32_16x16x32_bf16 v[32:35], v[164:167], v[188:191], v[32:35]
	v_mfma_f32_16x16x32_bf16 v[24:27], v[172:175], v[188:191], v[24:27]
	v_mfma_f32_16x16x32_bf16 v[20:23], v[164:167], v[196:199], v[20:23]
	v_mfma_f32_16x16x32_bf16 v[12:15], v[172:175], v[196:199], v[12:15]
	v_mfma_f32_16x16x32_bf16 v[4:7], v[164:167], v[216:219], v[4:7]
	v_mfma_f32_16x16x32_bf16 v[0:3], v[172:175], v[216:219], v[0:3]
	s_setprio 0
	s_barrier
	v_writelane_b32 v255, 0, 55
	s_add_i32 s58, s58, 2
	s_add_u32 s47, s47, 0x100
	s_addc_u32 s53, s53, 0
	s_add_u32 s30, s30, 0x100
	s_addc_u32 s31, s31, 0
	s_cmp_gt_u32 s58, 13
	s_cbranch_scc0 .LBB0_858
	v_readlane_b32 s80, v255, 28
	v_readlane_b32 s82, v255, 30
	s_and_b64 vcc, exec, s[12:13]
	s_mov_b32 s14, s82
	v_readlane_b32 s81, v255, 29
	v_readlane_b32 s83, v255, 31
	s_cbranch_vccz .LBB0_861
	s_barrier
